# EVENB item loop: next item's 10 row loads prefetched at the start of the current item (register staging + copies)
# speedup vs baseline: 1.0073x; 1.0020x over previous
.LBB0_578:
	s_or_b64 exec, exec, s[4:5]
	s_mov_b64 s[4:5], s[0:1]
	s_waitcnt lgkmcnt(0)
	s_barrier
	v_mbcnt_lo_u32_b32 v0, -1, 0
	v_mbcnt_hi_u32_b32 v0, -1, v0
	s_mov_b32 s6, s2
	v_add_u32_e32 v0, s3, v0
	s_cmpk_gt_i32 s6, 0x3ff
	v_readfirstlane_b32 s7, v0
	s_cbranch_scc1 .LBB0_583
	s_load_dwordx2 s[10:11], s[4:5], 0x90
	s_nop 0
	s_load_dwordx2 s[4:5], s[4:5], 0x40
	v_lshlrev_b32_e32 v2, 3, v0
	v_and_b32_e32 v2, 56, v2
	v_lshlrev_b32_e32 v168, 3, v2
	s_waitcnt lgkmcnt(0)
	s_add_u32 s12, s10, 0x8700000
	s_addc_u32 s13, s11, 0
	s_lshl_b32 s26, s38, 8
	s_lshl_b64 s[14:15], s[26:27], 2
	s_add_u32 s4, s4, s14
	s_addc_u32 s5, s5, s15
	v_ashrrev_i32_e32 v89, 3, v0
	v_lshl_add_u64 v[4:5], s[10:11], 0, v[168:169]
	s_mov_b64 s[14:15], 0x100000
	s_movk_i32 s17, 0x110
	v_and_b32_e32 v3, 31, v0
	v_bfe_u32 v8, v0, 5, 1
	v_lshl_add_u64 v[80:81], v[4:5], 0, s[14:15]
	v_mul_lo_u32 v4, v89, s17
	v_lshlrev_b32_e32 v5, 1, v2
	v_and_b32_e32 v1, 63, v0
	v_lshl_add_u32 v88, v3, 2, 0
	v_add3_u32 v90, 0, v4, v5
	v_mul_u32_u24_e32 v4, 0x10c, v3
	v_lshlrev_b32_e32 v5, 4, v8
	s_ashr_i32 s16, s7, 6
	v_add3_u32 v91, v88, v4, v5
	v_or_b32_e32 v4, 32, v1
	s_lshl_b32 s14, s16, 3
	v_mul_u32_u24_e32 v4, 0x110, v4
	v_add3_u32 v92, 0, v4, v5
	v_mov_b32_e32 v4, s14
	s_movk_i32 s14, 0xffe0
	v_bfi_b32 v93, s14, v4, v0
	v_mul_lo_u32 v0, v93, s17
	s_lshl_b32 s17, s16, 7
	v_lshlrev_b32_e32 v6, 2, v1
	v_add3_u32 v94, 0, v0, v5
	v_add_u32_e32 v0, 1, v93
	s_and_b32 s14, s17, 0xfffffe00
	v_cvt_f32_i32_e32 v95, v0
	v_or_b32_e32 v0, s14, v6
	s_lshl_b32 s7, s16, 5
	v_or_b32_e32 v0, 0x80, v0
	v_lshlrev_b32_e32 v4, 2, v8
	v_cmp_gt_u32_e32 vcc, 32, v1
	v_add_u32_e32 v96, 0, v0
	v_or_b32_e32 v0, s7, v1
	v_mov_b32_e32 v1, 0x180
	v_lshl_or_b32 v0, v0, 2, v1
	v_sub_u32_e32 v1, v93, v4
	v_subrev_u32_e32 v9, 32, v93
	v_sub_u32_e32 v11, 0, v1
	v_add_u32_e32 v7, 0, v6
	v_sub_u32_e32 v6, v9, v4
	v_max_i32_e32 v1, v1, v11
	v_cvt_f32_u32_e32 v98, v1
	v_sub_u32_e32 v1, 0, v6
	v_max_i32_e32 v1, v6, v1
	v_cvt_f32_u32_e32 v99, v1
	v_or_b32_e32 v1, 1, v4
	v_sub_u32_e32 v6, v93, v1
	v_sub_u32_e32 v11, 0, v6
	v_sub_u32_e32 v1, v9, v1
	v_max_i32_e32 v6, v6, v11
	v_cvt_f32_u32_e32 v100, v6
	v_sub_u32_e32 v6, 0, v1
	v_max_i32_e32 v1, v1, v6
	v_cvt_f32_u32_e32 v101, v1
	v_or_b32_e32 v1, 2, v4
	v_sub_u32_e32 v6, v93, v1
	v_sub_u32_e32 v12, 0, v6
	v_sub_u32_e32 v11, v9, v1
	v_max_i32_e32 v6, v6, v12
	v_cvt_f32_u32_e32 v102, v6
	v_sub_u32_e32 v6, 0, v11
	v_max_i32_e32 v6, v11, v6
	v_cvt_f32_u32_e32 v103, v6
	v_or_b32_e32 v6, 3, v4
	v_sub_u32_e32 v11, v93, v6
	v_sub_u32_e32 v12, 0, v11
	v_sub_u32_e32 v6, v9, v6
	v_max_i32_e32 v11, v11, v12
	v_cvt_f32_u32_e32 v104, v11
	v_sub_u32_e32 v11, 0, v6
	v_max_i32_e32 v6, v6, v11
	v_cvt_f32_u32_e32 v105, v6
	v_or_b32_e32 v6, 8, v4
	v_sub_u32_e32 v11, v93, v6
	v_sub_u32_e32 v12, 0, v11
	v_sub_u32_e32 v6, v9, v6
	v_max_i32_e32 v11, v11, v12
	v_cvt_f32_u32_e32 v106, v11
	v_sub_u32_e32 v11, 0, v6
	v_max_i32_e32 v6, v6, v11
	v_cvt_f32_u32_e32 v107, v6
	v_or_b32_e32 v6, 9, v4
	v_sub_u32_e32 v11, v93, v6
	v_sub_u32_e32 v12, 0, v11
	v_sub_u32_e32 v6, v9, v6
	v_max_i32_e32 v11, v11, v12
	v_cvt_f32_u32_e32 v108, v11
	v_sub_u32_e32 v11, 0, v6
	v_max_i32_e32 v6, v6, v11
	v_cvt_f32_u32_e32 v109, v6
	v_or_b32_e32 v6, 10, v4
	v_sub_u32_e32 v11, v93, v6
	v_sub_u32_e32 v12, 0, v11
	v_sub_u32_e32 v6, v9, v6
	v_max_i32_e32 v11, v11, v12
	v_cvt_f32_u32_e32 v110, v11
	v_sub_u32_e32 v11, 0, v6
	v_max_i32_e32 v6, v6, v11
	v_cvt_f32_u32_e32 v111, v6
	v_or_b32_e32 v6, 11, v4
	v_sub_u32_e32 v11, v93, v6
	v_sub_u32_e32 v12, 0, v11
	v_sub_u32_e32 v6, v9, v6
	v_max_i32_e32 v11, v11, v12
	v_cvt_f32_u32_e32 v112, v11
	v_sub_u32_e32 v11, 0, v6
	v_max_i32_e32 v6, v6, v11
	v_cvt_f32_u32_e32 v113, v6
	v_or_b32_e32 v6, 16, v4
	v_sub_u32_e32 v11, v93, v6
	v_sub_u32_e32 v12, 0, v11
	v_sub_u32_e32 v6, v9, v6
	v_max_i32_e32 v11, v11, v12
	v_cvt_f32_u32_e32 v114, v11
	v_sub_u32_e32 v11, 0, v6
	v_max_i32_e32 v6, v6, v11
	v_cvt_f32_u32_e32 v115, v6
	v_or_b32_e32 v6, 17, v4
	v_sub_u32_e32 v11, v93, v6
	v_sub_u32_e32 v12, 0, v11
	v_sub_u32_e32 v6, v9, v6
	v_max_i32_e32 v11, v11, v12
	v_cvt_f32_u32_e32 v116, v11
	v_sub_u32_e32 v11, 0, v6
	v_max_i32_e32 v6, v6, v11
	v_cvt_f32_u32_e32 v117, v6
	v_or_b32_e32 v6, 18, v4
	v_sub_u32_e32 v11, v93, v6
	v_sub_u32_e32 v12, 0, v11
	v_sub_u32_e32 v6, v9, v6
	v_max_i32_e32 v11, v11, v12
	v_cvt_f32_u32_e32 v118, v11
	v_sub_u32_e32 v11, 0, v6
	v_max_i32_e32 v6, v6, v11
	v_cvt_f32_u32_e32 v119, v6
	v_or_b32_e32 v6, 19, v4
	v_sub_u32_e32 v11, v93, v6
	v_sub_u32_e32 v12, 0, v11
	v_sub_u32_e32 v6, v9, v6
	v_max_i32_e32 v11, v11, v12
	v_cvt_f32_u32_e32 v120, v11
	v_sub_u32_e32 v11, 0, v6
	v_max_i32_e32 v6, v6, v11
	v_cvt_f32_u32_e32 v121, v6
	v_or_b32_e32 v6, 24, v4
	v_sub_u32_e32 v11, v93, v6
	v_sub_u32_e32 v12, 0, v11
	v_sub_u32_e32 v6, v9, v6
	v_max_i32_e32 v11, v11, v12
	v_cvt_f32_u32_e32 v122, v11
	v_sub_u32_e32 v11, 0, v6
	v_max_i32_e32 v6, v6, v11
	v_cvt_f32_u32_e32 v123, v6
	v_or_b32_e32 v6, 25, v4
	v_sub_u32_e32 v11, v93, v6
	v_sub_u32_e32 v12, 0, v11
	v_sub_u32_e32 v6, v9, v6
	v_max_i32_e32 v11, v11, v12
	v_cvt_f32_u32_e32 v124, v11
	v_sub_u32_e32 v11, 0, v6
	v_max_i32_e32 v6, v6, v11
	v_cvt_f32_u32_e32 v125, v6
	v_or_b32_e32 v6, 26, v4
	v_sub_u32_e32 v11, v93, v6
	v_sub_u32_e32 v12, 0, v11
	v_sub_u32_e32 v6, v9, v6
	v_max_i32_e32 v11, v11, v12
	s_and_b32 s15, s7, 0x60
	v_cvt_f32_u32_e32 v126, v11
	v_sub_u32_e32 v11, 0, v6
	v_add_u32_e32 v97, 0, v0
	v_or_b32_e32 v0, s15, v4
	v_max_i32_e32 v6, v6, v11
	v_or_b32_e32 v4, 27, v4
	v_cvt_f32_u32_e32 v127, v6
	v_sub_u32_e32 v6, v93, v4
	v_sub_u32_e32 v4, v9, v4
	v_sub_u32_e32 v9, 0, v6
	v_max_i32_e32 v6, v6, v9
	v_lshlrev_b32_e32 v168, 2, v0
	s_ashr_i32 s7, s6, 31
	v_or_b32_e32 v10, s15, v3
	v_cvt_f32_u32_e32 v128, v6
	v_sub_u32_e32 v6, 0, v4
	v_lshl_add_u64 v[82:83], s[4:5], 0, v[168:169]
	s_lshl_b64 s[4:5], s[6:7], 15
	s_lshl_b32 s7, s16, 13
	v_max_i32_e32 v4, v4, v6
	v_lshlrev_b32_e32 v6, 1, v10
	v_mul_u32_u24_e32 v1, 0x110, v1
	s_and_b32 s7, s7, 0x6000
	v_cvt_f32_u32_e32 v129, v4
	v_mul_u32_u24_e32 v4, 0x440, v8
	v_add3_u32 v131, 0, v1, v6
	v_lshl_or_b32 v1, v3, 8, s7
	v_add3_u32 v130, 0, v4, v6
	v_or3_b32 v4, s4, v5, v1
	v_mov_b32_e32 v5, s5
	v_lshl_add_u64 v[4:5], s[10:11], 0, v[4:5]
	s_mov_b64 s[4:5], 0x15700080
	v_add_u32_e32 v132, 0x660, v131
	v_add_u32_e32 v133, 0x880, v131
	v_add_u32_e32 v134, 0xee0, v131
	s_lshl_b32 s15, s6, 4
	v_lshl_add_u64 v[84:85], v[4:5], 0, s[4:5]
	v_lshlrev_b32_e32 v168, 1, v2
	v_add_u32_e32 v135, s17, v7
	v_lshlrev_b32_e32 v86, 1, v0
	s_mov_b32 s26, s6
	s_mov_b32 s17, s15
	s_and_b32 s100, s17, 0xffffffc0
	v_add_u32_e32 v152, s100, v89
	v_mov_b64_e32 v[150:151], s[12:13]
	v_mad_i64_i32 v[150:151], s[100:101], v152, s85, v[150:151]
	s_and_b32 s26, s26, 3
	s_lshl_b32 s26, s26, 8
	s_and_b32 s17, s17, 0xfc0
	v_add_u32_e32 v152, s17, v89
	v_lshl_add_u64 v[150:151], v[150:151], 0, s[26:27]
	v_ashrrev_i32_e32 v153, 31, v152
	v_lshl_add_u64 v[150:151], v[150:151], 0, v[168:169]
	v_lshlrev_b64 v[152:153], 9, v[152:153]
	s_mov_b32 s100, s86
	s_mov_b32 s101, 0
	global_load_dwordx4 v[208:211], v[150:151], off offset:3072
	global_load_dwordx4 v[212:215], v[150:151], off offset:3200
	v_lshl_add_u64 v[152:153], v[80:81], 0, v[152:153]
	v_lshl_add_u64 v[154:155], v[150:151], 0, s[100:101]
	global_load_dwordx4 v[204:207], v[152:153], off
	global_load_dwordx4 v[200:203], v[152:153], off offset:16
	global_load_dwordx4 v[192:195], v[152:153], off offset:32
	global_load_dwordx4 v[184:187], v[152:153], off offset:48
	global_load_dwordx4 v[196:199], v[154:155], off
	global_load_dwordx4 v[188:191], v[154:155], off offset:128
	global_load_dwordx4 v[176:179], v[154:155], off offset:1024
	global_load_dwordx4 v[180:183], v[154:155], off offset:1152
	s_waitcnt vmcnt(0)
	s_branch .LBB0_581

.LBB0_581:
	s_and_b32 s7, s15, 0xffffffc0
	s_and_b32 s16, s6, 3
	s_getpc_b64 s[4:5]
	s_add_u32 s4, s4, _ZN2mk5LOG2GE@rel32@lo+4
	s_addc_u32 s5, s5, _ZN2mk5LOG2GE@rel32@hi+12
	s_lshl_b32 s17, s16, 2
	s_load_dword s4, s[4:5], s17 offset:0x0
	s_lshl_b32 s16, s16, 7
	s_waitcnt vmcnt(1)
	v_mov_b32_e32 v0, v176
	v_mov_b32_e32 v1, v177
	v_mov_b32_e32 v2, v178
	v_mov_b32_e32 v3, v179
	v_mov_b32_e32 v4, v180
	v_mov_b32_e32 v5, v181
	v_mov_b32_e32 v6, v182
	v_mov_b32_e32 v7, v183
	v_mov_b32_e32 v8, v184
	v_mov_b32_e32 v9, v185
	v_mov_b32_e32 v10, v186
	v_mov_b32_e32 v11, v187
	v_mov_b32_e32 v12, v188
	v_mov_b32_e32 v13, v189
	v_mov_b32_e32 v14, v190
	v_mov_b32_e32 v15, v191
	v_mov_b32_e32 v16, v192
	v_mov_b32_e32 v17, v193
	v_mov_b32_e32 v18, v194
	v_mov_b32_e32 v19, v195
	v_mov_b32_e32 v20, v196
	v_mov_b32_e32 v21, v197
	v_mov_b32_e32 v22, v198
	v_mov_b32_e32 v23, v199
	v_mov_b32_e32 v24, v200
	v_mov_b32_e32 v25, v201
	v_mov_b32_e32 v26, v202
	v_mov_b32_e32 v27, v203
	v_mov_b32_e32 v28, v204
	v_mov_b32_e32 v29, v205
	v_mov_b32_e32 v30, v206
	v_mov_b32_e32 v31, v207
	v_mov_b32_e32 v32, v208
	v_mov_b32_e32 v33, v209
	v_mov_b32_e32 v34, v210
	v_mov_b32_e32 v35, v211
	v_mov_b32_e32 v36, v212
	v_mov_b32_e32 v37, v213
	v_mov_b32_e32 v38, v214
	v_mov_b32_e32 v39, v215
	s_add_i32 s26, s6, s24
	s_add_i32 s17, s15, s76
	s_cmpk_gt_i32 s26, 0x3ff
	s_cbranch_scc1 .Levenb_nopf
	s_and_b32 s100, s17, 0xffffffc0
	v_add_u32_e32 v152, s100, v89
	v_mov_b64_e32 v[150:151], s[12:13]
	v_mad_i64_i32 v[150:151], s[100:101], v152, s85, v[150:151]
	s_and_b32 s26, s26, 3
	s_lshl_b32 s26, s26, 8
	s_and_b32 s17, s17, 0xfc0
	v_add_u32_e32 v152, s17, v89
	v_lshl_add_u64 v[150:151], v[150:151], 0, s[26:27]
	v_ashrrev_i32_e32 v153, 31, v152
	v_lshl_add_u64 v[150:151], v[150:151], 0, v[168:169]
	v_lshlrev_b64 v[152:153], 9, v[152:153]
	s_mov_b32 s100, s86
	s_mov_b32 s101, 0
	global_load_dwordx4 v[208:211], v[150:151], off offset:3072
	global_load_dwordx4 v[212:215], v[150:151], off offset:3200
	v_lshl_add_u64 v[152:153], v[80:81], 0, v[152:153]
	v_lshl_add_u64 v[154:155], v[150:151], 0, s[100:101]
	global_load_dwordx4 v[204:207], v[152:153], off
	global_load_dwordx4 v[200:203], v[152:153], off offset:16
	global_load_dwordx4 v[192:195], v[152:153], off offset:32
	global_load_dwordx4 v[184:187], v[152:153], off offset:48
	global_load_dwordx4 v[196:199], v[154:155], off
	global_load_dwordx4 v[188:191], v[154:155], off offset:128
	global_load_dwordx4 v[176:179], v[154:155], off offset:1024
	global_load_dwordx4 v[180:183], v[154:155], off offset:1152
.Levenb_nopf:
	s_waitcnt lgkmcnt(0)
	v_mul_f32_e32 v76, s4, v122
	v_exp_f32_e32 v136, v76
	v_mul_f32_e32 v76, s4, v124
	v_exp_f32_e32 v137, v76
	v_mul_f32_e32 v76, s4, v126
	v_mul_f32_e32 v87, s4, v128
	v_exp_f32_e32 v138, v76
	v_exp_f32_e32 v139, v87
	v_lshlrev_b32_e32 v40, 16, v32
	v_and_b32_e32 v41, 0xffff0000, v32
	v_lshlrev_b32_e32 v42, 16, v36
	v_and_b32_e32 v43, 0xffff0000, v36
	v_mov_b32_e32 v44, v28
	v_mov_b32_e32 v45, v30
	v_mov_b32_e32 v30, v29
	v_lshlrev_b32_e32 v28, 16, v33
	v_and_b32_e32 v29, 0xffff0000, v33
	v_lshlrev_b32_e32 v32, 16, v37
	v_and_b32_e32 v33, 0xffff0000, v37
	v_mov_b32_e32 v47, v26
	v_mov_b32_e32 v26, v25
	v_lshlrev_b32_e32 v36, 16, v38
	v_and_b32_e32 v37, 0xffff0000, v38
	v_mov_b32_e32 v48, v16
	v_mov_b32_e32 v49, v18
	v_mov_b32_e32 v18, v17
	v_mov_b32_e32 v46, v24
	v_lshlrev_b32_e32 v24, 16, v34
	v_and_b32_e32 v25, 0xffff0000, v34
	v_lshlrev_b32_e32 v16, 16, v35
	v_and_b32_e32 v17, 0xffff0000, v35
	v_lshlrev_b32_e32 v34, 16, v39
	v_and_b32_e32 v35, 0xffff0000, v39
	v_mov_b32_e32 v50, v8
	v_mov_b32_e32 v51, v10
	v_mov_b32_e32 v10, v9
	v_pk_mul_f32 v[8:9], v[30:31], v[42:43]
	v_pk_mul_f32 v[38:39], v[44:45], v[42:43]
	v_pk_mul_f32 v[42:43], v[26:27], v[32:33]
	v_pk_mul_f32 v[52:53], v[18:19], v[36:37]
	v_pk_mul_f32 v[36:37], v[48:49], v[36:37]
	v_lshlrev_b32_e32 v58, 16, v12
	v_and_b32_e32 v59, 0xffff0000, v12
	v_pk_fma_f32 v[8:9], v[44:45], v[40:41], v[8:9] neg_lo:[0,0,1] neg_hi:[0,0,1]
	v_pk_fma_f32 v[38:39], v[30:31], v[40:41], v[38:39]
	v_pk_fma_f32 v[40:41], v[46:47], v[28:29], v[42:43] neg_lo:[0,0,1] neg_hi:[0,0,1]
	v_pk_fma_f32 v[42:43], v[48:49], v[24:25], v[52:53] neg_lo:[0,0,1] neg_hi:[0,0,1]
	v_pk_fma_f32 v[24:25], v[18:19], v[24:25], v[36:37]
	v_lshlrev_b32_e32 v12, 16, v13
	v_and_b32_e32 v13, 0xffff0000, v13
	v_pk_mul_f32 v[32:33], v[46:47], v[32:33]
	v_lshlrev_b32_e32 v56, 16, v20
	v_and_b32_e32 v57, 0xffff0000, v20
	v_cvt_pk_bf16_f32 v36, v38, v39
	v_cvt_pk_bf16_f32 v38, v24, v25
	v_lshlrev_b32_e32 v20, 16, v21
	v_and_b32_e32 v21, 0xffff0000, v21
	v_pk_mul_f32 v[24:25], v[26:27], v[12:13]
	v_pk_mul_f32 v[12:13], v[46:47], v[12:13]
	v_pk_fma_f32 v[28:29], v[26:27], v[28:29], v[32:33]
	v_pk_fma_f32 v[12:13], v[26:27], v[20:21], v[12:13]
	v_lshlrev_b32_e32 v26, 16, v14
	v_and_b32_e32 v27, 0xffff0000, v14
	v_cvt_pk_bf16_f32 v37, v28, v29
	v_pk_fma_f32 v[24:25], v[46:47], v[20:21], v[24:25] neg_lo:[0,0,1] neg_hi:[0,0,1]
	v_pk_mul_f32 v[20:21], v[12:13], s[40:41] op_sel_hi:[1,0]
	v_lshlrev_b32_e32 v12, 16, v22
	v_and_b32_e32 v13, 0xffff0000, v22
	v_pk_mul_f32 v[28:29], v[18:19], v[26:27]
	v_pk_mul_f32 v[26:27], v[48:49], v[26:27]
	v_pk_mul_f32 v[54:55], v[10:11], v[34:35]
	v_pk_mul_f32 v[34:35], v[50:51], v[34:35]
	v_pk_fma_f32 v[28:29], v[48:49], v[12:13], v[28:29] neg_lo:[0,0,1] neg_hi:[0,0,1]
	v_pk_fma_f32 v[12:13], v[18:19], v[12:13], v[26:27]
	v_lshlrev_b32_e32 v14, 16, v15
	v_and_b32_e32 v15, 0xffff0000, v15
	v_pk_fma_f32 v[52:53], v[50:51], v[16:17], v[54:55] neg_lo:[0,0,1] neg_hi:[0,0,1]
	v_pk_fma_f32 v[16:17], v[10:11], v[16:17], v[34:35]
	v_pk_mul_f32 v[54:55], v[30:31], v[58:59]
	v_pk_mul_f32 v[18:19], v[12:13], s[40:41] op_sel_hi:[1,0]
	v_lshlrev_b32_e32 v12, 16, v23
	v_and_b32_e32 v13, 0xffff0000, v23
	v_pk_mul_f32 v[22:23], v[10:11], v[14:15]
	v_cvt_pk_bf16_f32 v32, v8, v9
	v_cvt_pk_bf16_f32 v39, v16, v17
	v_pk_fma_f32 v[8:9], v[44:45], v[56:57], v[54:55] neg_lo:[0,0,1] neg_hi:[0,0,1]
	v_pk_mul_f32 v[16:17], v[44:45], v[58:59]
	v_pk_fma_f32 v[22:23], v[50:51], v[12:13], v[22:23] neg_lo:[0,0,1] neg_hi:[0,0,1]
	v_pk_mul_f32 v[14:15], v[50:51], v[14:15]
	v_pk_mul_f32 v[8:9], v[8:9], s[40:41] op_sel_hi:[1,0]
	v_pk_fma_f32 v[16:17], v[30:31], v[56:57], v[16:17]
	v_pk_mul_f32 v[24:25], v[24:25], s[40:41] op_sel_hi:[1,0]
	v_pk_mul_f32 v[28:29], v[28:29], s[40:41] op_sel_hi:[1,0]
	v_pk_mul_f32 v[22:23], v[22:23], s[40:41] op_sel_hi:[1,0]
	v_pk_fma_f32 v[10:11], v[10:11], v[12:13], v[14:15]
	v_cvt_pk_bf16_f32 v33, v40, v41
	v_cvt_pk_bf16_f32 v34, v42, v43
	v_cvt_pk_bf16_f32 v35, v52, v53
	v_pk_mul_f32 v[16:17], v[16:17], s[40:41] op_sel_hi:[1,0]
	v_pk_mul_f32 v[26:27], v[10:11], s[40:41] op_sel_hi:[1,0]
	v_cvt_pk_bf16_f32 v8, v8, v9
	v_cvt_pk_bf16_f32 v9, v24, v25
	v_cvt_pk_bf16_f32 v10, v28, v29
	v_cvt_pk_bf16_f32 v11, v22, v23
	ds_write_b128 v90, v[32:35]
	ds_write_b128 v90, v[36:39] offset:128
	v_cvt_pk_bf16_f32 v12, v16, v17
	v_cvt_pk_bf16_f32 v13, v20, v21
	v_cvt_pk_bf16_f32 v14, v18, v19
	v_cvt_pk_bf16_f32 v15, v26, v27
	ds_write_b128 v90, v[8:11] offset:17408
	ds_write_b128 v90, v[12:15] offset:17536
	ds_write_b128 v90, v[0:3] offset:34816
	ds_write_b128 v90, v[4:7] offset:34944
	s_waitcnt lgkmcnt(0)
	s_barrier
	ds_read_b128 v[0:3], v91 offset:17408
	ds_read_b128 v[32:35], v94
	ds_read_b128 v[36:39], v91 offset:17440
	ds_read_b128 v[52:55], v94 offset:32
	s_waitcnt lgkmcnt(2)
	v_mfma_f32_32x32x16_bf16 v[16:31], v[0:3], v[32:35], 0
	ds_read_b128 v[0:3], v92 offset:17408
	ds_read_b128 v[40:43], v92 offset:17440
	s_waitcnt lgkmcnt(1)
	v_mfma_f32_32x32x16_bf16 v[0:15], v[0:3], v[32:35], 0
	v_mfma_f32_32x32x16_bf16 v[16:31], v[36:39], v[52:55], v[16:31]
	s_waitcnt lgkmcnt(0)
	v_mfma_f32_32x32x16_bf16 v[0:15], v[40:43], v[52:55], v[0:15]
	ds_read_b128 v[36:39], v91 offset:17472
	ds_read_b128 v[56:59], v94 offset:64
	ds_read_b128 v[40:43], v91 offset:17504
	ds_read_b128 v[60:63], v94 offset:96
	s_waitcnt lgkmcnt(2)
	v_mfma_f32_32x32x16_bf16 v[16:31], v[36:39], v[56:59], v[16:31]
	ds_read_b128 v[36:39], v92 offset:17472
	ds_read_b128 v[44:47], v92 offset:17504
	s_waitcnt lgkmcnt(1)
	v_mfma_f32_32x32x16_bf16 v[0:15], v[36:39], v[56:59], v[0:15]
	v_mfma_f32_32x32x16_bf16 v[16:31], v[40:43], v[60:63], v[16:31]
	ds_read_b128 v[36:39], v91 offset:17536
	ds_read_b128 v[64:67], v94 offset:128
	ds_read_b128 v[40:43], v91 offset:17568
	ds_read_b128 v[68:71], v94 offset:160
	s_waitcnt lgkmcnt(4)
	v_mfma_f32_32x32x16_bf16 v[0:15], v[44:47], v[60:63], v[0:15]
	s_waitcnt lgkmcnt(2)
	v_mfma_f32_32x32x16_bf16 v[16:31], v[36:39], v[64:67], v[16:31]
	ds_read_b128 v[36:39], v92 offset:17536
	ds_read_b128 v[44:47], v92 offset:17568
	s_waitcnt lgkmcnt(1)
	v_mfma_f32_32x32x16_bf16 v[0:15], v[36:39], v[64:67], v[0:15]
	v_mfma_f32_32x32x16_bf16 v[16:31], v[40:43], v[68:71], v[16:31]
	ds_read_b128 v[36:39], v91 offset:17600
	ds_read_b128 v[72:75], v94 offset:192
	ds_read_b128 v[40:43], v91 offset:17632
	ds_read_b128 v[48:51], v94 offset:224
	s_waitcnt lgkmcnt(4)
	v_mfma_f32_32x32x16_bf16 v[0:15], v[44:47], v[68:71], v[0:15]
	s_waitcnt lgkmcnt(2)
	v_mfma_f32_32x32x16_bf16 v[16:31], v[36:39], v[72:75], v[16:31]
	ds_read_b128 v[36:39], v92 offset:17600
	ds_read_b128 v[44:47], v92 offset:17632
	global_load_dwordx4 v[76:79], v[84:85], off offset:-64
	s_waitcnt lgkmcnt(1)
	v_mfma_f32_32x32x16_bf16 v[0:15], v[36:39], v[72:75], v[0:15]
	v_mul_f32_e32 v36, s4, v98
	v_mul_f32_e32 v37, s4, v100
	v_exp_f32_e32 v36, v36
	v_exp_f32_e32 v37, v37
	v_mul_f32_e32 v38, s4, v99
	v_exp_f32_e32 v38, v38
	v_mfma_f32_32x32x16_bf16 v[16:31], v[40:43], v[48:51], v[16:31]
	s_waitcnt lgkmcnt(0)
	v_mfma_f32_32x32x16_bf16 v[0:15], v[44:47], v[48:51], v[0:15]
	s_nop 9
	v_mul_f32_e64 v16, v36, v16
	v_mul_f32_e64 v17, v37, v17
	v_mul_f32_e32 v36, s4, v101
	v_exp_f32_e32 v39, v36
	v_mul_f32_e32 v36, s4, v102
	v_exp_f32_e32 v40, v36
	v_mul_f32_e32 v36, s4, v104
	v_exp_f32_e32 v41, v36
	v_pk_mul_f32 v[36:37], v[38:39], v[0:1]
	v_mul_f32_e32 v0, s4, v103
	v_mul_f32_e32 v1, s4, v105
	v_exp_f32_e32 v0, v0
	v_exp_f32_e32 v1, v1
	v_mul_f32_e32 v38, s4, v106
	v_pk_mul_f32 v[18:19], v[40:41], v[18:19]
	v_exp_f32_e32 v40, v38
	v_mul_f32_e32 v38, s4, v108
	v_exp_f32_e32 v41, v38
	v_pk_mul_f32 v[38:39], v[0:1], v[2:3]
	v_mul_f32_e32 v0, s4, v107
	v_mul_f32_e32 v1, s4, v109
	v_exp_f32_e32 v0, v0
	v_exp_f32_e32 v1, v1
	v_mul_f32_e32 v2, s4, v110
	v_exp_f32_e32 v42, v2
	v_mul_f32_e32 v2, s4, v111
	v_exp_f32_e32 v44, v2
	v_mul_f32_e32 v2, s4, v112
	v_exp_f32_e32 v43, v2
	v_mul_f32_e32 v2, s4, v113
	v_pk_mul_f32 v[20:21], v[40:41], v[20:21]
	v_exp_f32_e32 v45, v2
	v_pk_mul_f32 v[40:41], v[0:1], v[4:5]
	global_load_dwordx4 v[0:3], v[84:85], off offset:-128
	v_mul_f32_e32 v4, s4, v114
	v_pk_mul_f32 v[46:47], v[42:43], v[22:23]
	v_exp_f32_e32 v22, v4
	v_mul_f32_e32 v4, s4, v116
	v_pk_mul_f32 v[42:43], v[44:45], v[6:7]
	v_exp_f32_e32 v23, v4
	global_load_dwordx4 v[4:7], v[84:85], off offset:-96
	v_mul_f32_e32 v44, s4, v118
	v_mul_f32_e32 v45, s4, v120
	v_exp_f32_e32 v44, v44
	v_exp_f32_e32 v45, v45
	v_pk_mul_f32 v[140:141], v[22:23], v[24:25]
	v_pk_mul_f32 v[144:145], v[136:137], v[28:29]
	v_pk_mul_f32 v[146:147], v[138:139], v[30:31]
	v_pk_mul_f32 v[142:143], v[44:45], v[26:27]
	ds_read_u16 v22, v130 offset:34816
	ds_read_u16 v23, v130 offset:35088
	ds_read_u16 v45, v130 offset:39712
	ds_read_u16 v87, v130 offset:39984
	ds_read_u16 v136, v130 offset:41344
	ds_read_u16 v137, v130 offset:41616
	ds_read_u16 v138, v130 offset:41888
	ds_read_u16 v139, v130 offset:42160
	s_waitcnt lgkmcnt(6)
	v_lshl_or_b32 v22, v23, 16, v22
	ds_read_u16 v23, v131 offset:34816
	ds_read_u16 v24, v131 offset:35088
	ds_read_u16 v25, v132 offset:34816
	ds_read_u16 v26, v132 offset:35088
	ds_read_u16 v27, v133 offset:34816
	ds_read_u16 v28, v133 offset:35088
	ds_read_u16 v44, v134 offset:34816
	ds_read_u16 v148, v134 offset:35088
	s_waitcnt lgkmcnt(6)
	v_lshl_or_b32 v23, v24, 16, v23
	s_waitcnt lgkmcnt(4)
	v_lshl_or_b32 v24, v26, 16, v25
	s_waitcnt lgkmcnt(2)
	v_lshl_or_b32 v25, v28, 16, v27
	v_cvt_pk_bf16_f32 v16, v16, v17
	v_cvt_pk_bf16_f32 v17, v18, v19
	v_cvt_pk_bf16_f32 v18, v20, v21
	v_cvt_pk_bf16_f32 v19, v46, v47
	s_waitcnt lgkmcnt(0)
	v_lshl_or_b32 v44, v148, 16, v44
	v_lshl_or_b32 v45, v87, 16, v45
	v_mfma_f32_32x32x16_bf16 v[16:31], v[22:25], v[16:19], 0
	v_lshl_or_b32 v46, v137, 16, v136
	v_lshl_or_b32 v47, v139, 16, v138
	v_cvt_pk_bf16_f32 v136, v140, v141
	v_cvt_pk_bf16_f32 v137, v142, v143
	v_cvt_pk_bf16_f32 v138, v144, v145
	v_cvt_pk_bf16_f32 v139, v146, v147
	v_cvt_pk_bf16_f32 v36, v36, v37
	v_cvt_pk_bf16_f32 v37, v38, v39
	v_mfma_f32_32x32x16_bf16 v[16:31], v[44:47], v[136:139], v[16:31]
	ds_read_u16 v44, v130 offset:43520
	ds_read_u16 v45, v130 offset:43792
	ds_read_u16 v46, v130 offset:44064
	ds_read_u16 v47, v130 offset:44336
	ds_read_u16 v87, v130 offset:45696
	ds_read_u16 v140, v130 offset:45968
	ds_read_u16 v141, v130 offset:46240
	ds_read_u16 v142, v130 offset:46512
	global_load_dwordx4 v[136:139], v[84:85], off offset:-32
	s_waitcnt lgkmcnt(6)
	v_lshl_or_b32 v44, v45, 16, v44
	s_waitcnt lgkmcnt(4)
	v_lshl_or_b32 v45, v47, 16, v46
	s_waitcnt lgkmcnt(2)
	v_lshl_or_b32 v46, v140, 16, v87
	s_waitcnt lgkmcnt(0)
	v_lshl_or_b32 v47, v142, 16, v141
	global_load_dwordx4 v[140:143], v[84:85], off
	v_cvt_pk_bf16_f32 v38, v40, v41
	v_cvt_pk_bf16_f32 v39, v42, v43
	s_nop 1
	v_mfma_f32_32x32x16_bf16 v[16:31], v[44:47], v[36:39], v[16:31]
	s_waitcnt vmcnt(3)
	v_mfma_f32_32x32x16_bf16 v[32:47], v[0:3], v[32:35], 0
	global_load_dwordx4 v[0:3], v[84:85], off offset:32
	s_waitcnt vmcnt(3)
	v_mfma_f32_32x32x16_bf16 v[32:47], v[4:7], v[52:55], v[32:47]
	global_load_dwordx4 v[4:7], v[84:85], off offset:64
	global_load_dwordx4 v[52:55], v[84:85], off offset:96
	v_mfma_f32_32x32x16_bf16 v[32:47], v[76:79], v[56:59], v[32:47]
	v_mul_f32_e32 v56, s4, v115
	v_mul_f32_e32 v57, s4, v117
	v_mul_f32_e32 v58, s4, v119
	v_mul_f32_e32 v59, s4, v121
	v_exp_f32_e32 v56, v56
	v_exp_f32_e32 v57, v57
	v_exp_f32_e32 v58, v58
	s_waitcnt vmcnt(4)
	v_mfma_f32_32x32x16_bf16 v[32:47], v[136:139], v[60:63], v[32:47]
	v_exp_f32_e32 v59, v59
	v_mul_f32_e32 v60, s4, v123
	v_mul_f32_e32 v61, s4, v125
	v_mul_f32_e32 v62, s4, v127
	v_mul_f32_e32 v63, s4, v129
	v_exp_f32_e32 v60, v60
	v_exp_f32_e32 v61, v61
	s_waitcnt vmcnt(3)
	v_mfma_f32_32x32x16_bf16 v[32:47], v[140:143], v[64:67], v[32:47]
	v_exp_f32_e32 v62, v62
	v_exp_f32_e32 v63, v63
	s_waitcnt vmcnt(2)
	v_mfma_f32_32x32x16_bf16 v[32:47], v[0:3], v[68:71], v[32:47]
	v_mul_f32_e64 v0, v56, v8
	v_mul_f32_e64 v1, v57, v9
	v_mul_f32_e64 v2, v58, v10
	v_mul_f32_e64 v3, v59, v11
	v_mul_f32_e64 v8, v60, v12
	v_mul_f32_e64 v9, v61, v13
	v_pk_mul_f32 v[10:11], v[62:63], v[14:15]
	v_cvt_pk_bf16_f32 v0, v0, v1
	v_cvt_pk_bf16_f32 v1, v2, v3
	s_waitcnt vmcnt(1)
	v_mfma_f32_32x32x16_bf16 v[32:47], v[4:7], v[72:75], v[32:47]
	ds_read_u16 v2, v130 offset:47872
	ds_read_u16 v3, v130 offset:48144
	ds_read_u16 v5, v130 offset:48416
	ds_read_u16 v6, v130 offset:48688
	ds_read_u16 v7, v130 offset:50048
	ds_read_u16 v12, v130 offset:50320
	ds_read_u16 v13, v130 offset:50592
	ds_read_u16 v14, v130 offset:50864
	s_waitcnt lgkmcnt(6)
	v_lshl_or_b32 v4, v3, 16, v2
	s_waitcnt lgkmcnt(4)
	v_lshl_or_b32 v5, v6, 16, v5
	s_waitcnt lgkmcnt(2)
	v_lshl_or_b32 v6, v12, 16, v7
	v_cvt_pk_bf16_f32 v2, v8, v9
	s_waitcnt lgkmcnt(0)
	v_lshl_or_b32 v7, v14, 16, v13
	v_cvt_pk_bf16_f32 v3, v10, v11
	s_waitcnt vmcnt(0)
	v_mfma_f32_32x32x16_bf16 v[32:47], v[52:55], v[48:51], v[32:47]
	v_mul_f32_e32 v8, s4, v95
	v_exp_f32_e32 v8, v8
	v_mfma_f32_32x32x16_bf16 v[16:31], v[4:7], v[0:3], v[16:31]
	s_nop 11
	v_pk_fma_f32 v[32:33], v[8:9], v[32:33], v[16:17] op_sel_hi:[0,1,1]
	v_pk_mul_f32 v[0:1], v[32:33], v[32:33]
	v_pk_fma_f32 v[18:19], v[8:9], v[34:35], v[18:19] op_sel_hi:[0,1,1]
	v_pk_mul_f32 v[2:3], v[18:19], v[18:19]
	v_add_f32_e32 v0, v0, v1
	v_pk_fma_f32 v[14:15], v[8:9], v[36:37], v[20:21] op_sel_hi:[0,1,1]
	v_add_f32_e32 v0, v2, v0
	v_pk_mul_f32 v[20:21], v[14:15], v[14:15]
	v_add_f32_e32 v0, v3, v0
	v_pk_fma_f32 v[16:17], v[8:9], v[38:39], v[22:23] op_sel_hi:[0,1,1]
	v_add_f32_e32 v0, v20, v0
	v_pk_mul_f32 v[22:23], v[16:17], v[16:17]
	v_add_f32_e32 v0, v21, v0
	v_pk_fma_f32 v[10:11], v[8:9], v[40:41], v[24:25] op_sel_hi:[0,1,1]
	v_add_f32_e32 v0, v22, v0
	v_pk_mul_f32 v[24:25], v[10:11], v[10:11]
	v_add_f32_e32 v0, v23, v0
	v_pk_fma_f32 v[12:13], v[8:9], v[42:43], v[26:27] op_sel_hi:[0,1,1]
	v_add_f32_e32 v0, v24, v0
	v_pk_mul_f32 v[26:27], v[12:13], v[12:13]
	v_add_f32_e32 v0, v25, v0
	v_pk_fma_f32 v[4:5], v[8:9], v[44:45], v[28:29] op_sel_hi:[0,1,1]
	v_add_f32_e32 v0, v26, v0
	v_pk_mul_f32 v[28:29], v[4:5], v[4:5]
	v_add_f32_e32 v0, v27, v0
	v_and_b32_e32 v2, 64, v254
	v_pk_fma_f32 v[6:7], v[8:9], v[46:47], v[30:31] op_sel_hi:[0,1,1]
	v_add_f32_e32 v0, v28, v0
	v_xor_b32_e32 v1, 32, v254
	v_add_u32_e32 v2, 64, v2
	v_pk_mul_f32 v[8:9], v[6:7], v[6:7]
	v_add_f32_e32 v0, v29, v0
	v_cmp_lt_i32_e64 s[4:5], v1, v2
	v_add_f32_e32 v0, v8, v0
	v_add_f32_e32 v0, v9, v0
	v_cndmask_b32_e64 v1, v254, v1, s[4:5]
	v_lshlrev_b32_e32 v1, 2, v1
	ds_bpermute_b32 v1, v1, v0
	s_and_saveexec_b64 s[4:5], vcc
	s_cbranch_execz .LBB0_580
	s_waitcnt lgkmcnt(0)
	v_add_f32_e32 v0, v0, v1
	ds_write_b32 v135, v0 offset:52224
	s_branch .LBB0_580
